# combined variant + A-loop m0 written early (hazard s_nop dropped)
# baseline (speedup 1.0000x reference)
.LBB0_563:
.LBB0_564:
.LBB0_566:
	ds_read_b128 v[64:67], v199 offset:40960
	ds_read_b128 v[220:223], v199 offset:45056
	s_mov_b32 m0, s43
	s_add_u32 s4, s92, 0x15658000
	s_addc_u32 s5, s93, 0
	global_load_lds_dwordx4 v164, s[4:5]
	s_waitcnt lgkmcnt(0)
	v_mfma_f32_32x32x16_bf16 v[80:95], v[64:67], v[132:135], v[48:63]
	ds_read_b128 v[68:71], v200 offset:40960
	ds_read_b128 v[224:227], v200 offset:45056
	s_setprio 1
	v_exp_f32_e32 v112, v112
	v_exp_f32_e32 v189, v113
	v_exp_f32_e32 v188, v114
	v_exp_f32_e32 v113, v115
	s_setprio 0
	s_mov_b32 m0, s70
	s_add_u32 s4, s92, 0x16618200
	s_addc_u32 s5, s93, 0
	global_load_lds_dwordx4 v160, s[4:5]
	s_waitcnt lgkmcnt(0)
	v_mfma_f32_32x32x16_bf16 v[80:95], v[68:71], v[128:131], v[80:95]
	ds_read_b128 v[228:231], v201 offset:40960
	ds_read_b128 v[232:235], v201 offset:45056
	s_setprio 1
	v_mfma_f32_32x32x16_bf16 v[64:79], v[220:223], v[132:135], v[48:63]
	v_exp_f32_e32 v114, v116
	v_exp_f32_e32 v117, v117
	v_exp_f32_e32 v116, v118
	v_exp_f32_e32 v115, v119
	s_setprio 0
	v_cvt_pk_bf16_f32 v220, v112, v189
	v_cvt_pk_bf16_f32 v221, v188, v113
	v_cvt_pk_bf16_f32 v222, v114, v117
	v_cvt_pk_bf16_f32 v223, v116, v115
	s_and_b64 vcc, exec, s[44:45]
	s_cbranch_vccnz .Lmy_a2_norope
	s_add_i32 m0, s43, 0x4000
	s_add_u32 s4, s92, 0x31d8500
	s_addc_u32 s5, s93, 0
	global_load_lds_dwordx4 v162, s[4:5]

.LBB0_572:
.LBB0_574:
	s_add_i32 s10, 0, 0x10000
	v_add_u32_e32 v172, s10, v212
	ds_read_b128 v[96:99], v199 offset:61440
	ds_read_b128 v[174:177], v172
	s_mov_b32 m0, s71
	s_add_u32 s4, s92, 0x15668000
	s_addc_u32 s5, s93, 0
	global_load_lds_dwordx4 v164, s[4:5]
	s_waitcnt lgkmcnt(0)
	v_mfma_f32_32x32x16_bf16 v[112:127], v[96:99], v[132:135], v[48:63]
	v_add_u32_e32 v220, s10, v214
	ds_read_b128 v[100:103], v200 offset:61440
	ds_read_b128 v[180:183], v220
	s_setprio 1
	v_exp_f32_e32 v80, v80
	v_exp_f32_e32 v189, v81
	v_exp_f32_e32 v188, v82
	v_exp_f32_e32 v81, v83
	s_setprio 0
	s_mov_b32 m0, s90
	s_add_u32 s4, s92, 0x16618280
	s_addc_u32 s5, s93, 0
	global_load_lds_dwordx4 v160, s[4:5]
	s_waitcnt lgkmcnt(0)
	v_mfma_f32_32x32x16_bf16 v[112:127], v[100:103], v[128:131], v[112:127]
	v_add_u32_e32 v221, s10, v216
	ds_read_b128 v[224:227], v201 offset:61440
	ds_read_b128 v[228:231], v221
	s_setprio 1
	v_mfma_f32_32x32x16_bf16 v[96:111], v[174:177], v[132:135], v[48:63]
	v_exp_f32_e32 v82, v84
	v_exp_f32_e32 v191, v85
	v_exp_f32_e32 v190, v86
	v_exp_f32_e32 v83, v87
	s_setprio 0
	v_cvt_pk_bf16_f32 v174, v80, v189
	v_cvt_pk_bf16_f32 v175, v188, v81
	v_cvt_pk_bf16_f32 v176, v82, v191
	v_cvt_pk_bf16_f32 v177, v190, v83
	s_and_b64 vcc, exec, s[44:45]
	s_cbranch_vccnz .Lmy_a3_norope
	s_add_i32 m0, s43, 0x9000
	s_add_u32 s4, s92, 0x32c8500
	s_addc_u32 s5, s93, 0
	global_load_lds_dwordx4 v162, s[4:5]

.LBB0_580:
.LBB0_582:
	ds_read_b128 v[64:67], v199
	ds_read_b128 v[174:177], v199 offset:4096
	s_mov_b32 m0, s91
	s_add_u32 s4, s92, 0x15678000
	s_addc_u32 s5, s93, 0
	global_load_lds_dwordx4 v164, s[4:5]
	s_waitcnt lgkmcnt(0)
	v_mfma_f32_32x32x16_bf16 v[80:95], v[64:67], v[132:135], v[48:63]
	ds_read_b128 v[68:71], v200
	ds_read_b128 v[180:183], v200 offset:4096
	s_setprio 1
	v_exp_f32_e32 v112, v112
	v_exp_f32_e32 v167, v113
	v_exp_f32_e32 v166, v114
	v_exp_f32_e32 v113, v115
	s_setprio 0
	s_mov_b32 m0, s95
	s_add_u32 s4, s92, 0x16618300
	s_addc_u32 s5, s93, 0
	global_load_lds_dwordx4 v160, s[4:5]
	s_waitcnt lgkmcnt(0)
	v_mfma_f32_32x32x16_bf16 v[80:95], v[68:71], v[128:131], v[80:95]
	ds_read_b128 v[188:191], v201
	ds_read_b128 v[192:195], v201 offset:4096
	s_setprio 1
	v_mfma_f32_32x32x16_bf16 v[64:79], v[174:177], v[132:135], v[48:63]
	v_exp_f32_e32 v114, v116
	v_exp_f32_e32 v169, v117
	v_exp_f32_e32 v168, v118
	v_exp_f32_e32 v115, v119
	s_setprio 0
	v_cvt_pk_bf16_f32 v174, v112, v167
	v_cvt_pk_bf16_f32 v175, v166, v113
	v_cvt_pk_bf16_f32 v176, v114, v169
	v_cvt_pk_bf16_f32 v177, v168, v115
	s_and_b64 vcc, exec, s[44:45]
	s_cbranch_vccnz .Lmy_a4_norope
	s_add_i32 m0, s43, 0xe000
	s_add_u32 s4, s92, 0x33b8500
	s_addc_u32 s5, s93, 0
	global_load_lds_dwordx4 v162, s[4:5]
